# hand-written first/last part of the fused final-norm epilogue (residual rows through a register ring, gain fetched early); exchange code unchanged
# speedup vs baseline: 1.0126x; 1.0011x over previous
.LBB0_793:
	s_lshl_b32 s11, s10, 8
	v_add_u32_e32 v176, s11, v178
	v_lshl_or_b32 v177, s36, 8, v180
	v_lshlrev_b32_e32 v176, 11, v176
	v_lshl_add_u32 v176, v177, 1, v176
	v_lshlrev_b32_e32 v177, 2, v177
	global_load_dwordx4 v[230:233], v177, s[84:85]
	global_load_dwordx4 v[234:237], v177, s[84:85] offset:16
	global_load_dwordx4 v[238:241], v177, s[84:85] offset:512
	global_load_dwordx4 v[242:245], v177, s[84:85] offset:528
	s_mov_b64 s[38:39], s[24:25]
	global_load_dwordx4 v[144:147], v176, s[38:39]
	global_load_dwordx4 v[148:151], v176, s[38:39] offset:256
	s_add_u32 s38, s24, 0x8000
	s_addc_u32 s39, s25, 0
	global_load_dwordx4 v[152:155], v176, s[38:39]
	global_load_dwordx4 v[156:159], v176, s[38:39] offset:256
	s_add_u32 s38, s24, 0x10000
	s_addc_u32 s39, s25, 0
	global_load_dwordx4 v[160:163], v176, s[38:39]
	global_load_dwordx4 v[164:167], v176, s[38:39] offset:256
	s_add_u32 s38, s24, 0x18000
	s_addc_u32 s39, s25, 0
	global_load_dwordx4 v[168:171], v176, s[38:39]
	global_load_dwordx4 v[172:175], v176, s[38:39] offset:256
	s_add_u32 s38, s24, 0x40000
	s_addc_u32 s39, s25, 0
	global_load_dwordx4 v[192:195], v176, s[38:39]
	global_load_dwordx4 v[196:199], v176, s[38:39] offset:256
	v_xor_b32_e32 v201, 16, v187
	v_xor_b32_e32 v249, 32, v187
	v_lshlrev_b32_e32 v201, 2, v201
	v_lshlrev_b32_e32 v249, 2, v249
	s_mov_b32 s41, 0xffff0000
	s_waitcnt vmcnt(8)
	v_lshlrev_b32_e32 v210, 16, v144
	v_and_b32_e32 v211, s41, v144
	v_lshlrev_b32_e32 v212, 16, v145
	v_and_b32_e32 v213, s41, v145
	v_lshlrev_b32_e32 v214, 16, v146
	v_and_b32_e32 v215, s41, v146
	v_lshlrev_b32_e32 v216, 16, v147
	v_and_b32_e32 v217, s41, v147
	v_pk_add_f32 v[124:125], v[124:125], v[210:211]
	v_pk_add_f32 v[126:127], v[126:127], v[212:213]
	v_pk_add_f32 v[120:121], v[120:121], v[214:215]
	v_pk_add_f32 v[122:123], v[122:123], v[216:217]
	v_lshlrev_b32_e32 v218, 16, v148
	v_and_b32_e32 v219, s41, v148
	v_lshlrev_b32_e32 v220, 16, v149
	v_and_b32_e32 v221, s41, v149
	v_lshlrev_b32_e32 v246, 16, v150
	v_and_b32_e32 v247, s41, v150
	v_lshlrev_b32_e32 v250, 16, v151
	v_and_b32_e32 v251, s41, v151
	v_pk_add_f32 v[116:117], v[116:117], v[218:219]
	v_pk_add_f32 v[118:119], v[118:119], v[220:221]
	v_pk_add_f32 v[112:113], v[112:113], v[246:247]
	v_pk_add_f32 v[114:115], v[114:115], v[250:251]
	s_add_u32 s38, s24, 0x48000
	s_addc_u32 s39, s25, 0
	global_load_dwordx4 v[144:147], v176, s[38:39]
	global_load_dwordx4 v[148:151], v176, s[38:39] offset:256
	v_pk_mul_f32 v[252:253], v[124:125], v[124:125]
	v_pk_mul_f32 v[254:255], v[126:127], v[126:127]
	v_pk_fma_f32 v[252:253], v[120:121], v[120:121], v[252:253]
	v_pk_fma_f32 v[254:255], v[122:123], v[122:123], v[254:255]
	v_pk_fma_f32 v[252:253], v[116:117], v[116:117], v[252:253]
	v_pk_fma_f32 v[254:255], v[118:119], v[118:119], v[254:255]
	v_pk_fma_f32 v[252:253], v[112:113], v[112:113], v[252:253]
	v_pk_fma_f32 v[254:255], v[114:115], v[114:115], v[254:255]
	v_pk_add_f32 v[252:253], v[252:253], v[254:255]
	s_nop 0
	v_add_f32_e32 v202, v252, v253
	s_waitcnt vmcnt(8)
	v_lshlrev_b32_e32 v210, 16, v152
	v_and_b32_e32 v211, s41, v152
	v_lshlrev_b32_e32 v212, 16, v153
	v_and_b32_e32 v213, s41, v153
	v_lshlrev_b32_e32 v214, 16, v154
	v_and_b32_e32 v215, s41, v154
	v_lshlrev_b32_e32 v216, 16, v155
	v_and_b32_e32 v217, s41, v155
	v_pk_add_f32 v[108:109], v[108:109], v[210:211]
	v_pk_add_f32 v[110:111], v[110:111], v[212:213]
	v_pk_add_f32 v[104:105], v[104:105], v[214:215]
	v_pk_add_f32 v[106:107], v[106:107], v[216:217]
	v_lshlrev_b32_e32 v218, 16, v156
	v_and_b32_e32 v219, s41, v156
	v_lshlrev_b32_e32 v220, 16, v157
	v_and_b32_e32 v221, s41, v157
	v_lshlrev_b32_e32 v246, 16, v158
	v_and_b32_e32 v247, s41, v158
	v_lshlrev_b32_e32 v250, 16, v159
	v_and_b32_e32 v251, s41, v159
	v_pk_add_f32 v[100:101], v[100:101], v[218:219]
	v_pk_add_f32 v[102:103], v[102:103], v[220:221]
	v_pk_add_f32 v[96:97], v[96:97], v[246:247]
	v_pk_add_f32 v[98:99], v[98:99], v[250:251]
	s_add_u32 s38, s24, 0x50000
	s_addc_u32 s39, s25, 0
	global_load_dwordx4 v[152:155], v176, s[38:39]
	global_load_dwordx4 v[156:159], v176, s[38:39] offset:256
	v_pk_mul_f32 v[252:253], v[108:109], v[108:109]
	v_pk_mul_f32 v[254:255], v[110:111], v[110:111]
	v_pk_fma_f32 v[252:253], v[104:105], v[104:105], v[252:253]
	v_pk_fma_f32 v[254:255], v[106:107], v[106:107], v[254:255]
	v_pk_fma_f32 v[252:253], v[100:101], v[100:101], v[252:253]
	v_pk_fma_f32 v[254:255], v[102:103], v[102:103], v[254:255]
	v_pk_fma_f32 v[252:253], v[96:97], v[96:97], v[252:253]
	v_pk_fma_f32 v[254:255], v[98:99], v[98:99], v[254:255]
	v_pk_add_f32 v[252:253], v[252:253], v[254:255]
	s_nop 0
	v_add_f32_e32 v203, v252, v253
	s_waitcnt vmcnt(8)
	v_lshlrev_b32_e32 v210, 16, v160
	v_and_b32_e32 v211, s41, v160
	v_lshlrev_b32_e32 v212, 16, v161
	v_and_b32_e32 v213, s41, v161
	v_lshlrev_b32_e32 v214, 16, v162
	v_and_b32_e32 v215, s41, v162
	v_lshlrev_b32_e32 v216, 16, v163
	v_and_b32_e32 v217, s41, v163
	v_pk_add_f32 v[92:93], v[92:93], v[210:211]
	v_pk_add_f32 v[94:95], v[94:95], v[212:213]
	v_pk_add_f32 v[88:89], v[88:89], v[214:215]
	v_pk_add_f32 v[90:91], v[90:91], v[216:217]
	v_lshlrev_b32_e32 v218, 16, v164
	v_and_b32_e32 v219, s41, v164
	v_lshlrev_b32_e32 v220, 16, v165
	v_and_b32_e32 v221, s41, v165
	v_lshlrev_b32_e32 v246, 16, v166
	v_and_b32_e32 v247, s41, v166
	v_lshlrev_b32_e32 v250, 16, v167
	v_and_b32_e32 v251, s41, v167
	v_pk_add_f32 v[84:85], v[84:85], v[218:219]
	v_pk_add_f32 v[86:87], v[86:87], v[220:221]
	v_pk_add_f32 v[80:81], v[80:81], v[246:247]
	v_pk_add_f32 v[82:83], v[82:83], v[250:251]
	s_add_u32 s38, s24, 0x58000
	s_addc_u32 s39, s25, 0
	global_load_dwordx4 v[160:163], v176, s[38:39]
	global_load_dwordx4 v[164:167], v176, s[38:39] offset:256
	v_pk_mul_f32 v[252:253], v[92:93], v[92:93]
	v_pk_mul_f32 v[254:255], v[94:95], v[94:95]
	v_pk_fma_f32 v[252:253], v[88:89], v[88:89], v[252:253]
	v_pk_fma_f32 v[254:255], v[90:91], v[90:91], v[254:255]
	v_pk_fma_f32 v[252:253], v[84:85], v[84:85], v[252:253]
	v_pk_fma_f32 v[254:255], v[86:87], v[86:87], v[254:255]
	v_pk_fma_f32 v[252:253], v[80:81], v[80:81], v[252:253]
	v_pk_fma_f32 v[254:255], v[82:83], v[82:83], v[254:255]
	v_pk_add_f32 v[252:253], v[252:253], v[254:255]
	s_nop 0
	v_add_f32_e32 v204, v252, v253
	s_waitcnt vmcnt(8)
	v_lshlrev_b32_e32 v210, 16, v168
	v_and_b32_e32 v211, s41, v168
	v_lshlrev_b32_e32 v212, 16, v169
	v_and_b32_e32 v213, s41, v169
	v_lshlrev_b32_e32 v214, 16, v170
	v_and_b32_e32 v215, s41, v170
	v_lshlrev_b32_e32 v216, 16, v171
	v_and_b32_e32 v217, s41, v171
	v_pk_add_f32 v[76:77], v[76:77], v[210:211]
	v_pk_add_f32 v[78:79], v[78:79], v[212:213]
	v_pk_add_f32 v[72:73], v[72:73], v[214:215]
	v_pk_add_f32 v[74:75], v[74:75], v[216:217]
	v_lshlrev_b32_e32 v218, 16, v172
	v_and_b32_e32 v219, s41, v172
	v_lshlrev_b32_e32 v220, 16, v173
	v_and_b32_e32 v221, s41, v173
	v_lshlrev_b32_e32 v246, 16, v174
	v_and_b32_e32 v247, s41, v174
	v_lshlrev_b32_e32 v250, 16, v175
	v_and_b32_e32 v251, s41, v175
	v_pk_add_f32 v[68:69], v[68:69], v[218:219]
	v_pk_add_f32 v[70:71], v[70:71], v[220:221]
	v_pk_add_f32 v[64:65], v[64:65], v[246:247]
	v_pk_add_f32 v[66:67], v[66:67], v[250:251]
	v_pk_mul_f32 v[252:253], v[76:77], v[76:77]
	v_pk_mul_f32 v[254:255], v[78:79], v[78:79]
	v_pk_fma_f32 v[252:253], v[72:73], v[72:73], v[252:253]
	v_pk_fma_f32 v[254:255], v[74:75], v[74:75], v[254:255]
	v_pk_fma_f32 v[252:253], v[68:69], v[68:69], v[252:253]
	v_pk_fma_f32 v[254:255], v[70:71], v[70:71], v[254:255]
	v_pk_fma_f32 v[252:253], v[64:65], v[64:65], v[252:253]
	v_pk_fma_f32 v[254:255], v[66:67], v[66:67], v[254:255]
	v_pk_add_f32 v[252:253], v[252:253], v[254:255]
	s_nop 0
	v_add_f32_e32 v205, v252, v253
	s_waitcnt vmcnt(6)
	v_lshlrev_b32_e32 v210, 16, v192
	v_and_b32_e32 v211, s41, v192
	v_lshlrev_b32_e32 v212, 16, v193
	v_and_b32_e32 v213, s41, v193
	v_lshlrev_b32_e32 v214, 16, v194
	v_and_b32_e32 v215, s41, v194
	v_lshlrev_b32_e32 v216, 16, v195
	v_and_b32_e32 v217, s41, v195
	v_pk_add_f32 v[60:61], v[60:61], v[210:211]
	v_pk_add_f32 v[62:63], v[62:63], v[212:213]
	v_pk_add_f32 v[56:57], v[56:57], v[214:215]
	v_pk_add_f32 v[58:59], v[58:59], v[216:217]
	v_lshlrev_b32_e32 v218, 16, v196
	v_and_b32_e32 v219, s41, v196
	v_lshlrev_b32_e32 v220, 16, v197
	v_and_b32_e32 v221, s41, v197
	v_lshlrev_b32_e32 v246, 16, v198
	v_and_b32_e32 v247, s41, v198
	v_lshlrev_b32_e32 v250, 16, v199
	v_and_b32_e32 v251, s41, v199
	v_pk_add_f32 v[52:53], v[52:53], v[218:219]
	v_pk_add_f32 v[54:55], v[54:55], v[220:221]
	v_pk_add_f32 v[48:49], v[48:49], v[246:247]
	v_pk_add_f32 v[50:51], v[50:51], v[250:251]
	v_pk_mul_f32 v[252:253], v[60:61], v[60:61]
	v_pk_mul_f32 v[254:255], v[62:63], v[62:63]
	v_pk_fma_f32 v[252:253], v[56:57], v[56:57], v[252:253]
	v_pk_fma_f32 v[254:255], v[58:59], v[58:59], v[254:255]
	v_pk_fma_f32 v[252:253], v[52:53], v[52:53], v[252:253]
	v_pk_fma_f32 v[254:255], v[54:55], v[54:55], v[254:255]
	v_pk_fma_f32 v[252:253], v[48:49], v[48:49], v[252:253]
	v_pk_fma_f32 v[254:255], v[50:51], v[50:51], v[254:255]
	v_pk_add_f32 v[252:253], v[252:253], v[254:255]
	s_nop 0
	v_add_f32_e32 v206, v252, v253
	s_waitcnt vmcnt(4)
	v_lshlrev_b32_e32 v210, 16, v144
	v_and_b32_e32 v211, s41, v144
	v_lshlrev_b32_e32 v212, 16, v145
	v_and_b32_e32 v213, s41, v145
	v_lshlrev_b32_e32 v214, 16, v146
	v_and_b32_e32 v215, s41, v146
	v_lshlrev_b32_e32 v216, 16, v147
	v_and_b32_e32 v217, s41, v147
	v_pk_add_f32 v[44:45], v[44:45], v[210:211]
	v_pk_add_f32 v[46:47], v[46:47], v[212:213]
	v_pk_add_f32 v[40:41], v[40:41], v[214:215]
	v_pk_add_f32 v[42:43], v[42:43], v[216:217]
	v_lshlrev_b32_e32 v218, 16, v148
	v_and_b32_e32 v219, s41, v148
	v_lshlrev_b32_e32 v220, 16, v149
	v_and_b32_e32 v221, s41, v149
	v_lshlrev_b32_e32 v246, 16, v150
	v_and_b32_e32 v247, s41, v150
	v_lshlrev_b32_e32 v250, 16, v151
	v_and_b32_e32 v251, s41, v151
	v_pk_add_f32 v[36:37], v[36:37], v[218:219]
	v_pk_add_f32 v[38:39], v[38:39], v[220:221]
	v_pk_add_f32 v[32:33], v[32:33], v[246:247]
	v_pk_add_f32 v[34:35], v[34:35], v[250:251]
	v_pk_mul_f32 v[252:253], v[44:45], v[44:45]
	v_pk_mul_f32 v[254:255], v[46:47], v[46:47]
	v_pk_fma_f32 v[252:253], v[40:41], v[40:41], v[252:253]
	v_pk_fma_f32 v[254:255], v[42:43], v[42:43], v[254:255]
	v_pk_fma_f32 v[252:253], v[36:37], v[36:37], v[252:253]
	v_pk_fma_f32 v[254:255], v[38:39], v[38:39], v[254:255]
	v_pk_fma_f32 v[252:253], v[32:33], v[32:33], v[252:253]
	v_pk_fma_f32 v[254:255], v[34:35], v[34:35], v[254:255]
	v_pk_add_f32 v[252:253], v[252:253], v[254:255]
	s_nop 0
	v_add_f32_e32 v207, v252, v253
	s_waitcnt vmcnt(2)
	v_lshlrev_b32_e32 v210, 16, v152
	v_and_b32_e32 v211, s41, v152
	v_lshlrev_b32_e32 v212, 16, v153
	v_and_b32_e32 v213, s41, v153
	v_lshlrev_b32_e32 v214, 16, v154
	v_and_b32_e32 v215, s41, v154
	v_lshlrev_b32_e32 v216, 16, v155
	v_and_b32_e32 v217, s41, v155
	v_pk_add_f32 v[28:29], v[28:29], v[210:211]
	v_pk_add_f32 v[30:31], v[30:31], v[212:213]
	v_pk_add_f32 v[24:25], v[24:25], v[214:215]
	v_pk_add_f32 v[26:27], v[26:27], v[216:217]
	v_lshlrev_b32_e32 v218, 16, v156
	v_and_b32_e32 v219, s41, v156
	v_lshlrev_b32_e32 v220, 16, v157
	v_and_b32_e32 v221, s41, v157
	v_lshlrev_b32_e32 v246, 16, v158
	v_and_b32_e32 v247, s41, v158
	v_lshlrev_b32_e32 v250, 16, v159
	v_and_b32_e32 v251, s41, v159
	v_pk_add_f32 v[20:21], v[20:21], v[218:219]
	v_pk_add_f32 v[22:23], v[22:23], v[220:221]
	v_pk_add_f32 v[16:17], v[16:17], v[246:247]
	v_pk_add_f32 v[18:19], v[18:19], v[250:251]
	v_pk_mul_f32 v[252:253], v[28:29], v[28:29]
	v_pk_mul_f32 v[254:255], v[30:31], v[30:31]
	v_pk_fma_f32 v[252:253], v[24:25], v[24:25], v[252:253]
	v_pk_fma_f32 v[254:255], v[26:27], v[26:27], v[254:255]
	v_pk_fma_f32 v[252:253], v[20:21], v[20:21], v[252:253]
	v_pk_fma_f32 v[254:255], v[22:23], v[22:23], v[254:255]
	v_pk_fma_f32 v[252:253], v[16:17], v[16:17], v[252:253]
	v_pk_fma_f32 v[254:255], v[18:19], v[18:19], v[254:255]
	v_pk_add_f32 v[252:253], v[252:253], v[254:255]
	s_nop 0
	v_add_f32_e32 v208, v252, v253
	s_waitcnt vmcnt(0)
	v_lshlrev_b32_e32 v210, 16, v160
	v_and_b32_e32 v211, s41, v160
	v_lshlrev_b32_e32 v212, 16, v161
	v_and_b32_e32 v213, s41, v161
	v_lshlrev_b32_e32 v214, 16, v162
	v_and_b32_e32 v215, s41, v162
	v_lshlrev_b32_e32 v216, 16, v163
	v_and_b32_e32 v217, s41, v163
	v_pk_add_f32 v[172:173], v[12:13], v[210:211]
	v_pk_add_f32 v[174:175], v[14:15], v[212:213]
	v_pk_add_f32 v[168:169], v[8:9], v[214:215]
	v_pk_add_f32 v[170:171], v[10:11], v[216:217]
	v_lshlrev_b32_e32 v218, 16, v164
	v_and_b32_e32 v219, s41, v164
	v_lshlrev_b32_e32 v220, 16, v165
	v_and_b32_e32 v221, s41, v165
	v_lshlrev_b32_e32 v246, 16, v166
	v_and_b32_e32 v247, s41, v166
	v_lshlrev_b32_e32 v250, 16, v167
	v_and_b32_e32 v251, s41, v167
	v_pk_add_f32 v[164:165], v[4:5], v[218:219]
	v_pk_add_f32 v[166:167], v[6:7], v[220:221]
	v_pk_add_f32 v[160:161], v[0:1], v[246:247]
	v_pk_add_f32 v[162:163], v[2:3], v[250:251]
	v_pk_mul_f32 v[252:253], v[172:173], v[172:173]
	v_pk_mul_f32 v[254:255], v[174:175], v[174:175]
	v_pk_fma_f32 v[252:253], v[168:169], v[168:169], v[252:253]
	v_pk_fma_f32 v[254:255], v[170:171], v[170:171], v[254:255]
	v_pk_fma_f32 v[252:253], v[164:165], v[164:165], v[252:253]
	v_pk_fma_f32 v[254:255], v[166:167], v[166:167], v[254:255]
	v_pk_fma_f32 v[252:253], v[160:161], v[160:161], v[252:253]
	v_pk_fma_f32 v[254:255], v[162:163], v[162:163], v[254:255]
	v_pk_add_f32 v[252:253], v[252:253], v[254:255]
	s_nop 0
	v_add_f32_e32 v209, v252, v253
	ds_bpermute_b32 v144, v201, v202
	ds_bpermute_b32 v145, v201, v203
	ds_bpermute_b32 v146, v201, v204
	ds_bpermute_b32 v147, v201, v205
	ds_bpermute_b32 v148, v201, v206
	ds_bpermute_b32 v149, v201, v207
	ds_bpermute_b32 v150, v201, v208
	ds_bpermute_b32 v151, v201, v209
	s_waitcnt lgkmcnt(7)
	v_add_f32_e32 v202, v202, v144
	s_waitcnt lgkmcnt(6)
	v_add_f32_e32 v203, v203, v145
	s_waitcnt lgkmcnt(5)
	v_add_f32_e32 v204, v204, v146
	s_waitcnt lgkmcnt(4)
	v_add_f32_e32 v205, v205, v147
	s_waitcnt lgkmcnt(3)
	v_add_f32_e32 v206, v206, v148
	s_waitcnt lgkmcnt(2)
	v_add_f32_e32 v207, v207, v149
	s_waitcnt lgkmcnt(1)
	v_add_f32_e32 v208, v208, v150
	s_waitcnt lgkmcnt(0)
	v_add_f32_e32 v209, v209, v151
	ds_bpermute_b32 v144, v249, v202
	ds_bpermute_b32 v145, v249, v203
	ds_bpermute_b32 v146, v249, v204
	ds_bpermute_b32 v147, v249, v205
	ds_bpermute_b32 v148, v249, v206
	ds_bpermute_b32 v149, v249, v207
	ds_bpermute_b32 v150, v249, v208
	ds_bpermute_b32 v151, v249, v209
	s_waitcnt lgkmcnt(7)
	v_add_f32_e32 v202, v202, v144
	s_waitcnt lgkmcnt(6)
	v_add_f32_e32 v203, v203, v145
	s_waitcnt lgkmcnt(5)
	v_add_f32_e32 v204, v204, v146
	s_waitcnt lgkmcnt(4)
	v_add_f32_e32 v205, v205, v147
	s_waitcnt lgkmcnt(3)
	v_add_f32_e32 v206, v206, v148
	s_waitcnt lgkmcnt(2)
	v_add_f32_e32 v207, v207, v149
	s_waitcnt lgkmcnt(1)
	v_add_f32_e32 v208, v208, v150
	s_waitcnt lgkmcnt(0)
	v_add_f32_e32 v209, v209, v151
	s_and_saveexec_b64 s[38:39], s[0:1]
	ds_write_b32 v191, v202
	ds_write_b32 v191, v203 offset:256
	ds_write_b32 v191, v204 offset:512
	ds_write_b32 v191, v205 offset:768
	ds_write_b32 v191, v206 offset:2048
	ds_write_b32 v191, v207 offset:2304
	ds_write_b32 v191, v208 offset:2560
	ds_write_b32 v191, v209 offset:2816
	s_or_b64 exec, exec, s[38:39]
	s_waitcnt lgkmcnt(0)
	s_barrier
	v_add_u32_e32 v0, s11, v181
	s_waitcnt lgkmcnt(0)
	v_ashrrev_i32_e32 v1, 31, v0
	s_and_saveexec_b64 s[38:39], s[8:9]
	s_cbranch_execz .LBB0_811
	ds_read_b128 v[2:5], v188
	s_ashr_i32 s37, s36, 31
	v_lshl_add_u64 v[6:7], v[0:1], 4, s[26:27]
	v_lshl_add_u64 v[6:7], s[36:37], 2, v[6:7]
	s_waitcnt lgkmcnt(0)
	v_mov_b32_e32 v8, v3
	v_mov_b32_e32 v9, v4
	v_mov_b32_e32 v3, v5
	v_pk_add_f32 v[2:3], v[8:9], v[2:3]
	s_nop 0
	v_pk_add_f32 v[2:3], v[2:3], v[2:3] op_sel:[0,1] op_sel_hi:[1,0]
	global_store_dword v[6:7], v2, off sc1

.LBB0_826:
	s_or_b64 exec, exec, s[36:37]
	s_waitcnt vmcnt(0) lgkmcnt(0)
	s_barrier
	ds_read2_b32 v[144:145], v183 offset1:16
	ds_read2_b32 v[146:147], v183 offset0:32 offset1:48
	ds_read2_b32 v[148:149], v183 offset0:128 offset1:144
	ds_read2_b32 v[150:151], v183 offset0:160 offset1:176
	v_lshlrev_b32_e32 v177, 1, v176
	s_waitcnt lgkmcnt(3)
	s_mov_b64 s[38:39], s[86:87]
	v_pk_mul_f32 v[124:125], v[124:125], v[144:145] op_sel:[0,0] op_sel_hi:[1,0]
	v_pk_mul_f32 v[126:127], v[126:127], v[144:145] op_sel:[0,0] op_sel_hi:[1,0]
	v_pk_mul_f32 v[120:121], v[120:121], v[144:145] op_sel:[0,0] op_sel_hi:[1,0]
	v_pk_mul_f32 v[122:123], v[122:123], v[144:145] op_sel:[0,0] op_sel_hi:[1,0]
	v_pk_mul_f32 v[124:125], v[124:125], v[230:231]
	v_pk_mul_f32 v[126:127], v[126:127], v[232:233]
	v_pk_mul_f32 v[120:121], v[120:121], v[234:235]
	v_pk_mul_f32 v[122:123], v[122:123], v[236:237]
	global_store_dwordx4 v177, v[124:127], s[38:39]
	global_store_dwordx4 v177, v[120:123], s[38:39] offset:16
	v_pk_mul_f32 v[116:117], v[116:117], v[144:145] op_sel:[0,0] op_sel_hi:[1,0]
	v_pk_mul_f32 v[118:119], v[118:119], v[144:145] op_sel:[0,0] op_sel_hi:[1,0]
	v_pk_mul_f32 v[112:113], v[112:113], v[144:145] op_sel:[0,0] op_sel_hi:[1,0]
	v_pk_mul_f32 v[114:115], v[114:115], v[144:145] op_sel:[0,0] op_sel_hi:[1,0]
	v_pk_mul_f32 v[116:117], v[116:117], v[238:239]
	v_pk_mul_f32 v[118:119], v[118:119], v[240:241]
	v_pk_mul_f32 v[112:113], v[112:113], v[242:243]
	v_pk_mul_f32 v[114:115], v[114:115], v[244:245]
	global_store_dwordx4 v177, v[116:119], s[38:39] offset:512
	global_store_dwordx4 v177, v[112:115], s[38:39] offset:528
	s_add_u32 s38, s86, 0x10000
	s_addc_u32 s39, s87, 0
	v_pk_mul_f32 v[108:109], v[108:109], v[144:145] op_sel:[0,1] op_sel_hi:[1,1]
	v_pk_mul_f32 v[110:111], v[110:111], v[144:145] op_sel:[0,1] op_sel_hi:[1,1]
	v_pk_mul_f32 v[104:105], v[104:105], v[144:145] op_sel:[0,1] op_sel_hi:[1,1]
	v_pk_mul_f32 v[106:107], v[106:107], v[144:145] op_sel:[0,1] op_sel_hi:[1,1]
	v_pk_mul_f32 v[108:109], v[108:109], v[230:231]
	v_pk_mul_f32 v[110:111], v[110:111], v[232:233]
	v_pk_mul_f32 v[104:105], v[104:105], v[234:235]
	v_pk_mul_f32 v[106:107], v[106:107], v[236:237]
	global_store_dwordx4 v177, v[108:111], s[38:39]
	global_store_dwordx4 v177, v[104:107], s[38:39] offset:16
	v_pk_mul_f32 v[100:101], v[100:101], v[144:145] op_sel:[0,1] op_sel_hi:[1,1]
	v_pk_mul_f32 v[102:103], v[102:103], v[144:145] op_sel:[0,1] op_sel_hi:[1,1]
	v_pk_mul_f32 v[96:97], v[96:97], v[144:145] op_sel:[0,1] op_sel_hi:[1,1]
	v_pk_mul_f32 v[98:99], v[98:99], v[144:145] op_sel:[0,1] op_sel_hi:[1,1]
	v_pk_mul_f32 v[100:101], v[100:101], v[238:239]
	v_pk_mul_f32 v[102:103], v[102:103], v[240:241]
	v_pk_mul_f32 v[96:97], v[96:97], v[242:243]
	v_pk_mul_f32 v[98:99], v[98:99], v[244:245]
	global_store_dwordx4 v177, v[100:103], s[38:39] offset:512
	global_store_dwordx4 v177, v[96:99], s[38:39] offset:528
	s_waitcnt lgkmcnt(2)
	s_add_u32 s38, s86, 0x20000
	s_addc_u32 s39, s87, 0
	v_pk_mul_f32 v[92:93], v[92:93], v[146:147] op_sel:[0,0] op_sel_hi:[1,0]
	v_pk_mul_f32 v[94:95], v[94:95], v[146:147] op_sel:[0,0] op_sel_hi:[1,0]
	v_pk_mul_f32 v[88:89], v[88:89], v[146:147] op_sel:[0,0] op_sel_hi:[1,0]
	v_pk_mul_f32 v[90:91], v[90:91], v[146:147] op_sel:[0,0] op_sel_hi:[1,0]
	v_pk_mul_f32 v[92:93], v[92:93], v[230:231]
	v_pk_mul_f32 v[94:95], v[94:95], v[232:233]
	v_pk_mul_f32 v[88:89], v[88:89], v[234:235]
	v_pk_mul_f32 v[90:91], v[90:91], v[236:237]
	global_store_dwordx4 v177, v[92:95], s[38:39]
	global_store_dwordx4 v177, v[88:91], s[38:39] offset:16
	v_pk_mul_f32 v[84:85], v[84:85], v[146:147] op_sel:[0,0] op_sel_hi:[1,0]
	v_pk_mul_f32 v[86:87], v[86:87], v[146:147] op_sel:[0,0] op_sel_hi:[1,0]
	v_pk_mul_f32 v[80:81], v[80:81], v[146:147] op_sel:[0,0] op_sel_hi:[1,0]
	v_pk_mul_f32 v[82:83], v[82:83], v[146:147] op_sel:[0,0] op_sel_hi:[1,0]
	v_pk_mul_f32 v[84:85], v[84:85], v[238:239]
	v_pk_mul_f32 v[86:87], v[86:87], v[240:241]
	v_pk_mul_f32 v[80:81], v[80:81], v[242:243]
	v_pk_mul_f32 v[82:83], v[82:83], v[244:245]
	global_store_dwordx4 v177, v[84:87], s[38:39] offset:512
	global_store_dwordx4 v177, v[80:83], s[38:39] offset:528
	s_add_u32 s38, s86, 0x30000
	s_addc_u32 s39, s87, 0
	v_pk_mul_f32 v[76:77], v[76:77], v[146:147] op_sel:[0,1] op_sel_hi:[1,1]
	v_pk_mul_f32 v[78:79], v[78:79], v[146:147] op_sel:[0,1] op_sel_hi:[1,1]
	v_pk_mul_f32 v[72:73], v[72:73], v[146:147] op_sel:[0,1] op_sel_hi:[1,1]
	v_pk_mul_f32 v[74:75], v[74:75], v[146:147] op_sel:[0,1] op_sel_hi:[1,1]
	v_pk_mul_f32 v[76:77], v[76:77], v[230:231]
	v_pk_mul_f32 v[78:79], v[78:79], v[232:233]
	v_pk_mul_f32 v[72:73], v[72:73], v[234:235]
	v_pk_mul_f32 v[74:75], v[74:75], v[236:237]
	global_store_dwordx4 v177, v[76:79], s[38:39]
	global_store_dwordx4 v177, v[72:75], s[38:39] offset:16
	v_pk_mul_f32 v[68:69], v[68:69], v[146:147] op_sel:[0,1] op_sel_hi:[1,1]
	v_pk_mul_f32 v[70:71], v[70:71], v[146:147] op_sel:[0,1] op_sel_hi:[1,1]
	v_pk_mul_f32 v[64:65], v[64:65], v[146:147] op_sel:[0,1] op_sel_hi:[1,1]
	v_pk_mul_f32 v[66:67], v[66:67], v[146:147] op_sel:[0,1] op_sel_hi:[1,1]
	v_pk_mul_f32 v[68:69], v[68:69], v[238:239]
	v_pk_mul_f32 v[70:71], v[70:71], v[240:241]
	v_pk_mul_f32 v[64:65], v[64:65], v[242:243]
	v_pk_mul_f32 v[66:67], v[66:67], v[244:245]
	global_store_dwordx4 v177, v[68:71], s[38:39] offset:512
	global_store_dwordx4 v177, v[64:67], s[38:39] offset:528
	s_waitcnt lgkmcnt(1)
	s_add_u32 s38, s86, 0x80000
	s_addc_u32 s39, s87, 0
	v_pk_mul_f32 v[60:61], v[60:61], v[148:149] op_sel:[0,0] op_sel_hi:[1,0]
	v_pk_mul_f32 v[62:63], v[62:63], v[148:149] op_sel:[0,0] op_sel_hi:[1,0]
	v_pk_mul_f32 v[56:57], v[56:57], v[148:149] op_sel:[0,0] op_sel_hi:[1,0]
	v_pk_mul_f32 v[58:59], v[58:59], v[148:149] op_sel:[0,0] op_sel_hi:[1,0]
	v_pk_mul_f32 v[60:61], v[60:61], v[230:231]
	v_pk_mul_f32 v[62:63], v[62:63], v[232:233]
	v_pk_mul_f32 v[56:57], v[56:57], v[234:235]
	v_pk_mul_f32 v[58:59], v[58:59], v[236:237]
	global_store_dwordx4 v177, v[60:63], s[38:39]
	global_store_dwordx4 v177, v[56:59], s[38:39] offset:16
	v_pk_mul_f32 v[52:53], v[52:53], v[148:149] op_sel:[0,0] op_sel_hi:[1,0]
	v_pk_mul_f32 v[54:55], v[54:55], v[148:149] op_sel:[0,0] op_sel_hi:[1,0]
	v_pk_mul_f32 v[48:49], v[48:49], v[148:149] op_sel:[0,0] op_sel_hi:[1,0]
	v_pk_mul_f32 v[50:51], v[50:51], v[148:149] op_sel:[0,0] op_sel_hi:[1,0]
	v_pk_mul_f32 v[52:53], v[52:53], v[238:239]
	v_pk_mul_f32 v[54:55], v[54:55], v[240:241]
	v_pk_mul_f32 v[48:49], v[48:49], v[242:243]
	v_pk_mul_f32 v[50:51], v[50:51], v[244:245]
	global_store_dwordx4 v177, v[52:55], s[38:39] offset:512
	global_store_dwordx4 v177, v[48:51], s[38:39] offset:528
	s_add_u32 s38, s86, 0x90000
	s_addc_u32 s39, s87, 0
	v_pk_mul_f32 v[44:45], v[44:45], v[148:149] op_sel:[0,1] op_sel_hi:[1,1]
	v_pk_mul_f32 v[46:47], v[46:47], v[148:149] op_sel:[0,1] op_sel_hi:[1,1]
	v_pk_mul_f32 v[40:41], v[40:41], v[148:149] op_sel:[0,1] op_sel_hi:[1,1]
	v_pk_mul_f32 v[42:43], v[42:43], v[148:149] op_sel:[0,1] op_sel_hi:[1,1]
	v_pk_mul_f32 v[44:45], v[44:45], v[230:231]
	v_pk_mul_f32 v[46:47], v[46:47], v[232:233]
	v_pk_mul_f32 v[40:41], v[40:41], v[234:235]
	v_pk_mul_f32 v[42:43], v[42:43], v[236:237]
	global_store_dwordx4 v177, v[44:47], s[38:39]
	global_store_dwordx4 v177, v[40:43], s[38:39] offset:16
	v_pk_mul_f32 v[36:37], v[36:37], v[148:149] op_sel:[0,1] op_sel_hi:[1,1]
	v_pk_mul_f32 v[38:39], v[38:39], v[148:149] op_sel:[0,1] op_sel_hi:[1,1]
	v_pk_mul_f32 v[32:33], v[32:33], v[148:149] op_sel:[0,1] op_sel_hi:[1,1]
	v_pk_mul_f32 v[34:35], v[34:35], v[148:149] op_sel:[0,1] op_sel_hi:[1,1]
	v_pk_mul_f32 v[36:37], v[36:37], v[238:239]
	v_pk_mul_f32 v[38:39], v[38:39], v[240:241]
	v_pk_mul_f32 v[32:33], v[32:33], v[242:243]
	v_pk_mul_f32 v[34:35], v[34:35], v[244:245]
	global_store_dwordx4 v177, v[36:39], s[38:39] offset:512
	global_store_dwordx4 v177, v[32:35], s[38:39] offset:528
	s_waitcnt lgkmcnt(0)
	s_add_u32 s38, s86, 0xa0000
	s_addc_u32 s39, s87, 0
	v_pk_mul_f32 v[28:29], v[28:29], v[150:151] op_sel:[0,0] op_sel_hi:[1,0]
	v_pk_mul_f32 v[30:31], v[30:31], v[150:151] op_sel:[0,0] op_sel_hi:[1,0]
	v_pk_mul_f32 v[24:25], v[24:25], v[150:151] op_sel:[0,0] op_sel_hi:[1,0]
	v_pk_mul_f32 v[26:27], v[26:27], v[150:151] op_sel:[0,0] op_sel_hi:[1,0]
	v_pk_mul_f32 v[28:29], v[28:29], v[230:231]
	v_pk_mul_f32 v[30:31], v[30:31], v[232:233]
	v_pk_mul_f32 v[24:25], v[24:25], v[234:235]
	v_pk_mul_f32 v[26:27], v[26:27], v[236:237]
	global_store_dwordx4 v177, v[28:31], s[38:39]
	global_store_dwordx4 v177, v[24:27], s[38:39] offset:16
	v_pk_mul_f32 v[20:21], v[20:21], v[150:151] op_sel:[0,0] op_sel_hi:[1,0]
	v_pk_mul_f32 v[22:23], v[22:23], v[150:151] op_sel:[0,0] op_sel_hi:[1,0]
	v_pk_mul_f32 v[16:17], v[16:17], v[150:151] op_sel:[0,0] op_sel_hi:[1,0]
	v_pk_mul_f32 v[18:19], v[18:19], v[150:151] op_sel:[0,0] op_sel_hi:[1,0]
	v_pk_mul_f32 v[20:21], v[20:21], v[238:239]
	v_pk_mul_f32 v[22:23], v[22:23], v[240:241]
	v_pk_mul_f32 v[16:17], v[16:17], v[242:243]
	v_pk_mul_f32 v[18:19], v[18:19], v[244:245]
	global_store_dwordx4 v177, v[20:23], s[38:39] offset:512
	global_store_dwordx4 v177, v[16:19], s[38:39] offset:528
	s_add_u32 s38, s86, 0xb0000
	s_addc_u32 s39, s87, 0
	v_pk_mul_f32 v[172:173], v[172:173], v[150:151] op_sel:[0,1] op_sel_hi:[1,1]
	v_pk_mul_f32 v[174:175], v[174:175], v[150:151] op_sel:[0,1] op_sel_hi:[1,1]
	v_pk_mul_f32 v[168:169], v[168:169], v[150:151] op_sel:[0,1] op_sel_hi:[1,1]
	v_pk_mul_f32 v[170:171], v[170:171], v[150:151] op_sel:[0,1] op_sel_hi:[1,1]
	v_pk_mul_f32 v[172:173], v[172:173], v[230:231]
	v_pk_mul_f32 v[174:175], v[174:175], v[232:233]
	v_pk_mul_f32 v[168:169], v[168:169], v[234:235]
	v_pk_mul_f32 v[170:171], v[170:171], v[236:237]
	global_store_dwordx4 v177, v[172:175], s[38:39]
	global_store_dwordx4 v177, v[168:171], s[38:39] offset:16
	v_pk_mul_f32 v[164:165], v[164:165], v[150:151] op_sel:[0,1] op_sel_hi:[1,1]
	v_pk_mul_f32 v[166:167], v[166:167], v[150:151] op_sel:[0,1] op_sel_hi:[1,1]
	v_pk_mul_f32 v[160:161], v[160:161], v[150:151] op_sel:[0,1] op_sel_hi:[1,1]
	v_pk_mul_f32 v[162:163], v[162:163], v[150:151] op_sel:[0,1] op_sel_hi:[1,1]
	v_pk_mul_f32 v[164:165], v[164:165], v[238:239]
	v_pk_mul_f32 v[166:167], v[166:167], v[240:241]
	v_pk_mul_f32 v[160:161], v[160:161], v[242:243]
	v_pk_mul_f32 v[162:163], v[162:163], v[244:245]
	global_store_dwordx4 v177, v[164:167], s[38:39] offset:512
	global_store_dwordx4 v177, v[160:163], s[38:39] offset:528
	s_andn2_b64 vcc, exec, s[6:7]
	s_mov_b64 s[6:7], -1
	s_waitcnt lgkmcnt(0)
	s_cbranch_vccnz .LBB0_782
	s_andn2_b64 vcc, exec, s[16:17]
	s_cbranch_vccnz .LBB0_781
	s_barrier
	s_branch .LBB0_781
